# grid barrier: waiters poll the top-level arrival counter (>= target) so the release needs no second atomic after the last leader's arrival round trip
# speedup vs baseline: 1.0046x; 1.0037x over previous
.LBB0_1132:
	s_or_b64 exec, exec, s[8:9]
	v_cvt_f32_u32_e32 v5, v3
	s_waitcnt vmcnt(0)
	v_readfirstlane_b32 s6, v4
	v_sub_u32_e32 v4, 0, v3
	v_rcp_iflag_f32_e32 v5, v5
	v_add_u32_e32 v6, s6, v0
	v_mul_f32_e32 v5, 0x4f7ffffe, v5
	v_cvt_u32_f32_e32 v5, v5
	v_mul_lo_u32 v0, v4, v5
	v_mul_hi_u32 v0, v5, v0
	v_add_u32_e32 v0, v5, v0
	v_mul_hi_u32 v0, v6, v0
	v_mul_lo_u32 v4, v0, v3
	v_sub_u32_e32 v4, v6, v4
	v_add_u32_e32 v5, 1, v0
	v_cmp_ge_u32_e32 vcc, v4, v3
	s_nop 1
	v_cndmask_b32_e32 v0, v0, v5, vcc
	v_sub_u32_e32 v5, v4, v3
	v_cndmask_b32_e32 v4, v4, v5, vcc
	v_add_u32_e32 v5, 1, v0
	v_cmp_ge_u32_e32 vcc, v4, v3
	v_add_u32_e32 v4, 1, v6
	s_nop 0
	v_cndmask_b32_e32 v0, v0, v5, vcc
	v_mul_lo_u32 v5, v3, v0
	v_add_u32_e32 v3, v5, v3
	v_cmp_ne_u32_e32 vcc, v4, v3
	s_and_saveexec_b64 s[6:7], vcc
	s_xor_b64 s[6:7], exec, s[6:7]
	s_movk_i32 s46, 0x1000
	s_cbranch_execz .LBB0_1146
	s_waitcnt lgkmcnt(0)
	buffer_inv sc1
	s_add_u32 s12, s2, 0x83400
	s_addc_u32 s13, s3, 0
	v_add_u32_e32 v4, 1, v0
	v_mul_lo_u32 v4, v4, v2
	global_load_dword v2, v1, s[12:13] sc1
	s_waitcnt vmcnt(0)
	v_cmp_lt_u32_e32 vcc, v2, v4
	s_and_saveexec_b64 s[8:9], vcc
	s_cbranch_execz .LBB0_1145
	s_add_u32 s10, s2, 0x80200
	s_addc_u32 s11, s3, 0
	s_mov_b32 s24, 1
	s_mov_b64 s[14:15], 0
	s_branch .LBB0_1136

.LBB0_1140:
	global_load_dword v2, v1, s[12:13] sc1
	s_add_i32 s24, s24, 1
	s_mov_b64 s[20:21], -1
	s_waitcnt vmcnt(0)
	v_cmp_ge_u32_e32 vcc, v2, v4
	s_orn2_b64 s[18:19], vcc, exec
	s_branch .LBB0_1135

.LBB0_1149:
	s_or_b64 exec, exec, s[8:9]
	s_waitcnt vmcnt(0)
	v_readfirstlane_b32 s6, v3
	v_sub_u32_e32 v4, 0, v2
	s_mov_b64 s[10:11], 0
	v_add_u32_e32 v3, s6, v0
	v_cvt_f32_u32_e32 v0, v2
	s_add_u32 s6, s2, 0x83400
	s_addc_u32 s7, s3, 0
	v_rcp_iflag_f32_e32 v0, v0
	s_nop 0
	v_mul_f32_e32 v0, 0x4f7ffffe, v0
	v_cvt_u32_f32_e32 v0, v0
	v_mul_lo_u32 v4, v4, v0
	v_mul_hi_u32 v4, v0, v4
	v_add_u32_e32 v0, v0, v4
	v_mul_hi_u32 v0, v3, v0
	v_mul_lo_u32 v4, v0, v2
	v_sub_u32_e32 v4, v3, v4
	v_cmp_ge_u32_e32 vcc, v4, v2
	v_add_u32_e32 v5, 1, v0
	v_add_u32_e32 v3, 1, v3
	v_cndmask_b32_e32 v0, v0, v5, vcc
	v_sub_u32_e32 v5, v4, v2
	v_cndmask_b32_e32 v4, v4, v5, vcc
	v_cmp_ge_u32_e32 vcc, v4, v2
	v_add_u32_e32 v4, 1, v0
	s_nop 0
	v_cndmask_b32_e32 v0, v0, v4, vcc
	v_mul_lo_u32 v4, v2, v0
	v_add_u32_e32 v2, v4, v2
	v_mov_b32_e32 v4, v2
	v_cmp_ne_u32_e32 vcc, v3, v2
	v_mov_b64_e32 v[2:3], s[6:7]
	s_and_saveexec_b64 s[8:9], vcc
	s_cbranch_execz .LBB0_1161
	s_mov_b32 s24, 1
	buffer_inv sc1
	global_load_dword v2, v1, s[6:7] sc1
	s_mov_b64 s[14:15], 0
	s_waitcnt vmcnt(0)
	v_cmp_lt_u32_e32 vcc, v2, v4
	s_and_saveexec_b64 s[12:13], vcc
	s_cbranch_execz .LBB0_1160
	s_add_u32 s10, s2, 0x80200
	s_addc_u32 s11, s3, 0
	s_mov_b32 s22, 1
	s_mov_b64 s[2:3], 0
	s_branch .LBB0_1153

.LBB0_1157:
	global_load_dword v2, v1, s[6:7] sc1
	s_add_i32 s22, s22, 1
	s_mov_b64 s[18:19], -1
	s_waitcnt vmcnt(0)
	v_cmp_ge_u32_e32 vcc, v2, v4
	s_orn2_b64 s[16:17], vcc, exec
	s_branch .LBB0_1152
